# v75 + prologue A: block-diagonal pool weight build also dealt to the converter workgroups only
# baseline (speedup 1.0000x reference)
; #define GAS __attribute__((address_space(1)))
; __device__ __forceinline__ unsigned f2bf(float f) { unsigned u = __builtin_bit_cast(unsigned, f); return (u + 0x7fffu + ((u >> 16) & 1u)) >> 16; }
; __device__ __forceinline__ void pro_a(Frame& F, CArgs a, unsigned long long& tm_acc) {
;     ...
;         GAS bf16_t* wpt = (GAS bf16_t*)(ws + WS_WPT);
;         for (int e = F.blk * 512 + F.tid; e < DEPTH * 512 * 512; e += F.G * 512) {
;             const int l = e >> 18, n = (e >> 9) & 511, k = e & 511; float v = 0.f;
;             if ((n >> 7) == (k >> 7)) v = ((const GAS float*)a->in[I_POOLW])[(((size_t)l * 4 + (n >> 7)) * 128 + (k & 127)) * 128 + (n & 127)] * ((const GAS float*)a->in[I_POOLS])[l * 512 + n];
;             wpt[e] = (bf16_t)f2bf(v);
;         }
.LBB0_202:
	s_waitcnt vmcnt(23)
	s_sub_i32 s100, s2, 0x90
	s_cmpk_lt_i32 s2, 0x90
	s_cselect_b32 s100, 0x1000, s100
	v_lshl_add_u32 v2, s100, 9, v0
	s_mov_b32 s4, 0x100000
	v_cmp_gt_i32_e32 vcc, s4, v2
	s_and_saveexec_b64 s[4:5], vcc
	s_cbranch_execz .LBB0_207
	s_mov_b32 s6, 0xe000
	v_ashrrev_i32_e32 v3, 31, v2
	s_waitcnt vmcnt(22)
	v_lshl_add_u64 v[8:9], v[2:3], 1, s[36:37]
	s_mov_b64 s[8:9], 0x3800000
	s_ashr_i32 s7, s6, 31
	v_and_b32_e32 v4, 0x7f, v0
	v_mov_b32_e32 v7, 0
	v_lshl_add_u64 v[8:9], v[8:9], 0, s[8:9]
	s_lshl_b64 s[8:9], s[6:7], 1
	s_mov_b64 s[10:11], 0
	s_movk_i32 s7, 0x180
	s_movk_i32 s14, 0x7fff
	s_mov_b32 s15, 0xfffff
	s_branch .LBB0_205
